# attention loops: one independent MFMA hoisted into the v_cmp -> s_cbranch_vccnz gap at each rescale test (asm guide 7.12)
# speedup vs baseline: 1.0006x; 1.0006x over previous
; DEVI float ex2(float x) { return __builtin_amdgcn_exp2f(x); }
; template <int DK>
; DEVI void attn_tile(const char* kb, const char* vb, const bool first, const bf16x8 (&qf)[2][DK / 32], f32x4 (&o)[2][4],
;                     float (&mrun)[2], float (&lsum)[2], const int l15, const int quad) {
;     ...
;   for (int qt = 0; qt < 2; ++qt)
; #pragma unroll
;     for (int ks = 0; ks < 4; ++ks) { const float nm = -mrun[qt]; s[qt][ks] = f32x4{nm, nm, nm, nm}; }
; #pragma unroll
;   for (int ks = 0; ks < 4; ++ks)
; #pragma unroll
;     for (int kk = 0; kk < NKK; ++kk) {
;       bf16x8 kf = *reinterpret_cast<const bf16x8*>(kb + (ks * 16 + l15) * KSTR + (kk * 32 + quad * 8) * 2);
;       s[0][ks] = mfma16(kf, qf[0][kk], s[0][ks]);
;       s[1][ks] = mfma16(kf, qf[1][kk], s[1][ks]);
;     }
;   bf16x8 pf[2][2];
; #pragma unroll
;   for (int qt = 0; qt < 2; ++qt) {
;     float mx = fmaxf(fmaxf(s[qt][0][0], s[qt][0][1]), fmaxf(s[qt][0][2], s[qt][0][3]));
; #pragma unroll
;     for (int ks = 1; ks < 4; ++ks) mx = fmaxf(mx, fmaxf(fmaxf(s[qt][ks][0], s[qt][ks][1]), fmaxf(s[qt][ks][2], s[qt][ks][3])));
;     if (__any(first || (mx > 8.f))) {
;       float rm = fmaxf(mx, __shfl_xor(mx, 16));
;       rm = fmaxf(rm, __shfl_xor(rm, 32));
;       const float delta = first ? rm : fmaxf(rm, 0.f);
;       const float alpha = first ? 1.f : ex2(-delta);
;       mrun[qt] += delta;
;       lsum[qt] *= alpha;
; #pragma unroll
;       for (int ks = 0; ks < 4; ++ks)
; #pragma unroll
;         for (int j = 0; j < 4; ++j) s[qt][ks][j] -= delta;
; #pragma unroll
;       for (int dd = 0; dd < 4; ++dd)
; #pragma unroll
;         for (int j = 0; j < 4; ++j) o[qt][dd][j] *= alpha;
;     }
;     float ps = 0.f;
; #pragma unroll
;     for (int ks = 0; ks < 4; ++ks)
; #pragma unroll
;       for (int j = 0; j < 4; ++j) { float pv = ex2(s[qt][ks][j]); s[qt][ks][j] = pv; ps += pv; }
;     lsum[qt] += ps;
; #pragma unroll
;     for (int k2 = 0; k2 < 2; ++k2) {
;       u32x4 wv;
;       wv[0] = pack2(s[qt][2 * k2][0], s[qt][2 * k2][1]);
;       wv[1] = pack2(s[qt][2 * k2][2], s[qt][2 * k2][3]);
;       wv[2] = pack2(s[qt][2 * k2 + 1][0], s[qt][2 * k2 + 1][1]);
;       wv[3] = pack2(s[qt][2 * k2 + 1][2], s[qt][2 * k2 + 1][3]);
;       pf[qt][k2] = as_bf8(wv);
;     }
;   }
; #pragma unroll
;   for (int dd = 0; dd < 4; ++dd)
; #pragma unroll
;     for (int k2 = 0; k2 < 2; ++k2) {
.Lgqa_loop_g:
	v_add_u32_e32 v211, s18, v168
	ds_read_b128 v[100:103], v211
	ds_read_b128 v[104:107], v211 offset:64
	global_load_dwordx4 v[192:195], v204, s[12:13]
	global_load_dwordx4 v[196:199], v205, s[12:13]
	global_load_dwordx4 v[244:247], v206, s[22:23]
	global_load_dwordx4 v[164:167], v207, s[22:23]
	s_add_i32 s96, s11, 2
	s_cmp_lt_i32 s96, s3
	s_cselect_b32 s96, 0x2000, 0
	s_cselect_b32 s17, 0x80, 0
	s_add_u32 s12, s12, s96
	s_addc_u32 s13, s13, 0
	s_add_u32 s22, s22, s17
	s_addc_u32 s23, s23, 0
	ds_read_b128 v[108:111], v211 offset:2560
	ds_read_b128 v[112:115], v211 offset:2624
	ds_read_b128 v[116:119], v211 offset:5120
	ds_read_b128 v[120:123], v211 offset:5184
	ds_read_b128 v[124:127], v211 offset:7680
	ds_read_b128 v[128:131], v211 offset:7744
	s_setprio 1
	s_waitcnt lgkmcnt(7)
	v_mfma_f32_16x16x32_bf16 v[132:135], v[100:103], v[4:7], v[228:231]
	s_waitcnt lgkmcnt(6)
	v_mfma_f32_16x16x32_bf16 v[132:135], v[104:107], v[12:15], v[132:135]
	s_waitcnt lgkmcnt(4)
	v_mfma_f32_16x16x32_bf16 v[136:139], v[108:111], v[4:7], v[228:231]
	v_mfma_f32_16x16x32_bf16 v[136:139], v[112:115], v[12:15], v[136:139]
	s_waitcnt lgkmcnt(2)
	v_mfma_f32_16x16x32_bf16 v[140:143], v[116:119], v[4:7], v[228:231]
	v_mfma_f32_16x16x32_bf16 v[140:143], v[120:123], v[12:15], v[140:143]
	s_waitcnt lgkmcnt(0)
	v_mfma_f32_16x16x32_bf16 v[144:147], v[124:127], v[4:7], v[228:231]
	v_mfma_f32_16x16x32_bf16 v[144:147], v[128:131], v[12:15], v[144:147]
	v_mfma_f32_16x16x32_bf16 v[212:215], v[100:103], v[8:11], v[236:239]
	v_mfma_f32_16x16x32_bf16 v[212:215], v[104:107], v[16:19], v[212:215]
	v_max3_f32 v153, v132, v133, v134
	v_max3_f32 v154, v135, v136, v137
	v_mfma_f32_16x16x32_bf16 v[216:219], v[108:111], v[8:11], v[236:239]
	v_max3_f32 v155, v138, v139, v140
	v_max3_f32 v156, v141, v142, v143
	v_mfma_f32_16x16x32_bf16 v[216:219], v[112:115], v[16:19], v[216:219]
	s_nop 0
	v_max3_f32 v153, v153, v154, v144
	v_max3_f32 v155, v155, v156, v145
	v_max3_f32 v153, v153, v155, v146
	v_max_f32_e32 v153, v153, v147
	v_cmp_lt_f32_e32 vcc, 0x41000000, v153
	v_mfma_f32_16x16x32_bf16 v[220:223], v[116:119], v[8:11], v[236:239]
	s_cbranch_vccnz .Lgqa_rare0_ga
.Lgqa_join0_ga:
	v_add_u32_e32 v208, s18, v169
	ds_read_b64 v[100:101], v208 offset:0
	ds_read_b64 v[102:103], v208 offset:32
	ds_read_b64 v[104:105], v208 offset:2304
	ds_read_b64 v[106:107], v208 offset:2336
	ds_read_b64 v[108:109], v208 offset:4608
	ds_read_b64 v[110:111], v208 offset:4640
	ds_read_b64 v[112:113], v208 offset:6912
	ds_read_b64 v[114:115], v208 offset:6944
	v_exp_f32_e32 v132, v132
	v_exp_f32_e32 v133, v133
	v_exp_f32_e32 v134, v134
	v_exp_f32_e32 v135, v135
	v_add_f32_e32 v154, v132, v133
	v_exp_f32_e32 v136, v136
	v_add_f32_e32 v155, v134, v135
	v_exp_f32_e32 v137, v137
	v_exp_f32_e32 v138, v138
	v_add_f32_e32 v154, v154, v136
	v_mfma_f32_16x16x32_bf16 v[220:223], v[120:123], v[16:19], v[220:223]
	v_exp_f32_e32 v139, v139
	v_add_f32_e32 v155, v155, v137
	v_exp_f32_e32 v140, v140
	v_add_f32_e32 v154, v154, v138
	v_exp_f32_e32 v141, v141
	v_add_f32_e32 v155, v155, v139
	v_exp_f32_e32 v142, v142
	v_add_f32_e32 v154, v154, v140
	v_exp_f32_e32 v143, v143
	v_add_f32_e32 v155, v155, v141
	v_mfma_f32_16x16x32_bf16 v[224:227], v[124:127], v[8:11], v[236:239]
	v_exp_f32_e32 v144, v144
	v_add_f32_e32 v154, v154, v142
	v_exp_f32_e32 v145, v145
	v_add_f32_e32 v155, v155, v143
	v_exp_f32_e32 v146, v146
	v_add_f32_e32 v154, v154, v144
	v_exp_f32_e32 v147, v147
	v_add_f32_e32 v155, v155, v145
	v_add_f32_e32 v154, v154, v146
	v_add_f32_e32 v155, v155, v147
	v_mfma_f32_16x16x32_bf16 v[224:227], v[128:131], v[16:19], v[224:227]
	v_add_f32_e32 v154, v154, v155
	v_add_f32_e32 v176, v176, v154
	v_cvt_pk_bf16_f32 v228, v132, v133
	v_cvt_pk_bf16_f32 v229, v134, v135
	v_cvt_pk_bf16_f32 v230, v136, v137
	v_cvt_pk_bf16_f32 v231, v138, v139
	v_cvt_pk_bf16_f32 v232, v140, v141
	v_cvt_pk_bf16_f32 v233, v142, v143
	v_cvt_pk_bf16_f32 v234, v144, v145
	v_cvt_pk_bf16_f32 v235, v146, v147
	ds_read_b64 v[116:117], v208 offset:64
	ds_read_b64 v[118:119], v208 offset:96
	ds_read_b64 v[120:121], v208 offset:2368
	ds_read_b64 v[122:123], v208 offset:2400
	ds_read_b64 v[124:125], v208 offset:4672
	ds_read_b64 v[126:127], v208 offset:4704
	ds_read_b64 v[128:129], v208 offset:6976
	ds_read_b64 v[130:131], v208 offset:7008
	v_max3_f32 v153, v212, v213, v214
	v_max3_f32 v154, v215, v216, v217
	v_max3_f32 v155, v218, v219, v220
	v_max3_f32 v156, v221, v222, v223
	s_setprio 0
	s_waitcnt lgkmcnt(12)
	v_mfma_f32_16x16x32_bf16 v[52:55], v[100:103], v[228:231], v[52:55]
	v_max3_f32 v153, v153, v154, v224
	v_max3_f32 v155, v155, v156, v225
	v_mfma_f32_16x16x32_bf16 v[56:59], v[104:107], v[228:231], v[56:59]
	v_max3_f32 v153, v153, v155, v226
	v_max_f32_e32 v153, v153, v227
	v_cmp_lt_f32_e32 vcc, 0x41000000, v153
	s_waitcnt lgkmcnt(8)
	v_mfma_f32_16x16x32_bf16 v[60:63], v[108:111], v[228:231], v[60:63]
	s_cbranch_vccnz .Lgqa_rare1_ga
; DEVI unsigned pack2(float a, float b) { f32x2_t v = {a, b}; bf16x2_t r = __builtin_convertvector(v, bf16x2_t); return *reinterpret_cast<unsigned*>(&r); }
; DEVI float ex2(float x) { return __builtin_amdgcn_exp2f(x); }
; template <int DK>
; DEVI void attn_tile(const char* kb, const char* vb, const bool first, const bf16x8 (&qf)[2][DK / 32], f32x4 (&o)[2][4],
;                     float (&mrun)[2], float (&lsum)[2], const int l15, const int quad) {
;     ...
;   for (int qt = 0; qt < 2; ++qt)
; #pragma unroll
;     for (int ks = 0; ks < 4; ++ks) { const float nm = -mrun[qt]; s[qt][ks] = f32x4{nm, nm, nm, nm}; }
; #pragma unroll
;   for (int ks = 0; ks < 4; ++ks)
; #pragma unroll
;     for (int kk = 0; kk < NKK; ++kk) {
;       bf16x8 kf = *reinterpret_cast<const bf16x8*>(kb + (ks * 16 + l15) * KSTR + (kk * 32 + quad * 8) * 2);
;       s[0][ks] = mfma16(kf, qf[0][kk], s[0][ks]);
;       s[1][ks] = mfma16(kf, qf[1][kk], s[1][ks]);
;     }
;   bf16x8 pf[2][2];
; #pragma unroll
;   for (int qt = 0; qt < 2; ++qt) {
;     float mx = fmaxf(fmaxf(s[qt][0][0], s[qt][0][1]), fmaxf(s[qt][0][2], s[qt][0][3]));
; #pragma unroll
;     for (int ks = 1; ks < 4; ++ks) mx = fmaxf(mx, fmaxf(fmaxf(s[qt][ks][0], s[qt][ks][1]), fmaxf(s[qt][ks][2], s[qt][ks][3])));
;     if (__any(first || (mx > 8.f))) {
;     ...
;     float ps = 0.f;
; #pragma unroll
;     for (int ks = 0; ks < 4; ++ks)
; #pragma unroll
;       for (int j = 0; j < 4; ++j) { float pv = ex2(s[qt][ks][j]); s[qt][ks][j] = pv; ps += pv; }
;     lsum[qt] += ps;
; #pragma unroll
;     for (int k2 = 0; k2 < 2; ++k2) {
;       u32x4 wv;
;       wv[0] = pack2(s[qt][2 * k2][0], s[qt][2 * k2][1]);
;       wv[1] = pack2(s[qt][2 * k2][2], s[qt][2 * k2][3]);
;       wv[2] = pack2(s[qt][2 * k2 + 1][0], s[qt][2 * k2 + 1][1]);
;       wv[3] = pack2(s[qt][2 * k2 + 1][2], s[qt][2 * k2 + 1][3]);
;       pf[qt][k2] = as_bf8(wv);
;     }
;   }
; #pragma unroll
;   for (int dd = 0; dd < 4; ++dd)
; #pragma unroll
;     for (int k2 = 0; k2 < 2; ++k2) {
;       u32x2 lo = *reinterpret_cast<const u32x2*>(vb + (dd * 16 + l15) * 144 + (k2 * 32 + quad * 4) * 2);
;       u32x2 hi = *reinterpret_cast<const u32x2*>(vb + (dd * 16 + l15) * 144 + (k2 * 32 + 16 + quad * 4) * 2);
;       u32x4 vv = {lo[0], lo[1], hi[0], hi[1]};
;       bf16x8 vf = as_bf8(vv);
;       o[0][dd] = mfma16(vf, pf[0][k2], o[0][dd]);
;       o[1][dd] = mfma16(vf, pf[1][k2], o[1][dd]);
;     }
.Lgqa_join1_ga:
	v_exp_f32_e32 v212, v212
	v_exp_f32_e32 v213, v213
	v_exp_f32_e32 v214, v214
	v_exp_f32_e32 v215, v215
	v_add_f32_e32 v154, v212, v213
	v_exp_f32_e32 v216, v216
	v_mfma_f32_16x16x32_bf16 v[64:67], v[112:115], v[228:231], v[64:67]
	v_add_f32_e32 v155, v214, v215
	v_exp_f32_e32 v217, v217
	v_exp_f32_e32 v218, v218
	v_add_f32_e32 v154, v154, v216
	v_exp_f32_e32 v219, v219
	v_add_f32_e32 v155, v155, v217
	v_exp_f32_e32 v220, v220
	s_waitcnt lgkmcnt(4)
	v_mfma_f32_16x16x32_bf16 v[52:55], v[116:119], v[232:235], v[52:55]
	v_add_f32_e32 v154, v154, v218
	v_exp_f32_e32 v221, v221
	v_add_f32_e32 v155, v155, v219
	v_exp_f32_e32 v222, v222
	v_add_f32_e32 v154, v154, v220
	v_exp_f32_e32 v223, v223
	v_add_f32_e32 v155, v155, v221
	v_mfma_f32_16x16x32_bf16 v[56:59], v[120:123], v[232:235], v[56:59]
	v_exp_f32_e32 v224, v224
	v_add_f32_e32 v154, v154, v222
	v_exp_f32_e32 v225, v225
	v_add_f32_e32 v155, v155, v223
	v_exp_f32_e32 v226, v226
	v_add_f32_e32 v154, v154, v224
	s_waitcnt lgkmcnt(0)
	v_mfma_f32_16x16x32_bf16 v[60:63], v[124:127], v[232:235], v[60:63]
	v_exp_f32_e32 v227, v227
	v_add_f32_e32 v155, v155, v225
	v_add_f32_e32 v154, v154, v226
	v_add_f32_e32 v155, v155, v227
	v_add_f32_e32 v154, v154, v155
	v_add_f32_e32 v175, v175, v154
	v_cvt_pk_bf16_f32 v236, v212, v213
	v_mfma_f32_16x16x32_bf16 v[64:67], v[128:131], v[232:235], v[64:67]
	v_cvt_pk_bf16_f32 v237, v214, v215
	v_cvt_pk_bf16_f32 v238, v216, v217
	v_cvt_pk_bf16_f32 v239, v218, v219
	v_cvt_pk_bf16_f32 v240, v220, v221
	v_cvt_pk_bf16_f32 v241, v222, v223
	v_cvt_pk_bf16_f32 v242, v224, v225
	v_cvt_pk_bf16_f32 v243, v226, v227
	s_nop 0
	v_mfma_f32_16x16x32_bf16 v[36:39], v[100:103], v[236:239], v[36:39]
	v_mfma_f32_16x16x32_bf16 v[40:43], v[104:107], v[236:239], v[40:43]
	v_mfma_f32_16x16x32_bf16 v[44:47], v[108:111], v[236:239], v[44:47]
	v_mfma_f32_16x16x32_bf16 v[48:51], v[112:115], v[236:239], v[48:51]
	v_xor_b32_e32 v228, 0x80000000, v172
	v_mov_b32_e32 v229, v228
	v_mfma_f32_16x16x32_bf16 v[36:39], v[116:119], v[240:243], v[36:39]
	v_mfma_f32_16x16x32_bf16 v[40:43], v[120:123], v[240:243], v[40:43]
	v_mfma_f32_16x16x32_bf16 v[44:47], v[124:127], v[240:243], v[44:47]
	v_mfma_f32_16x16x32_bf16 v[48:51], v[128:131], v[240:243], v[48:51]
	v_mov_b32_e32 v230, v228
	v_mov_b32_e32 v231, v228
	v_xor_b32_e32 v236, 0x80000000, v173
	v_mov_b32_e32 v237, v236
	v_mov_b32_e32 v238, v236
	v_mov_b32_e32 v239, v236
	v_add_u32_e32 v211, s18, v168
	ds_read_b128 v[100:103], v211
	ds_read_b128 v[104:107], v211 offset:64
	ds_read_b128 v[108:111], v211 offset:2560
	ds_read_b128 v[112:115], v211 offset:2624
	ds_read_b128 v[116:119], v211 offset:5120
	ds_read_b128 v[120:123], v211 offset:5184
	ds_read_b128 v[124:127], v211 offset:7680
	ds_read_b128 v[128:131], v211 offset:7744
	s_setprio 1
	s_waitcnt lgkmcnt(7)
	v_mfma_f32_16x16x32_bf16 v[132:135], v[100:103], v[20:23], v[228:231]
	s_waitcnt lgkmcnt(6)
	v_mfma_f32_16x16x32_bf16 v[132:135], v[104:107], v[24:27], v[132:135]
	s_waitcnt lgkmcnt(4)
	v_mfma_f32_16x16x32_bf16 v[136:139], v[108:111], v[20:23], v[228:231]
	v_mfma_f32_16x16x32_bf16 v[136:139], v[112:115], v[24:27], v[136:139]
	s_waitcnt lgkmcnt(2)
	v_mfma_f32_16x16x32_bf16 v[140:143], v[116:119], v[20:23], v[228:231]
	v_mfma_f32_16x16x32_bf16 v[140:143], v[120:123], v[24:27], v[140:143]
	s_waitcnt lgkmcnt(0)
	v_mfma_f32_16x16x32_bf16 v[144:147], v[124:127], v[20:23], v[228:231]
	v_mfma_f32_16x16x32_bf16 v[144:147], v[128:131], v[24:27], v[144:147]
	v_mfma_f32_16x16x32_bf16 v[212:215], v[100:103], v[28:31], v[236:239]
	v_mfma_f32_16x16x32_bf16 v[212:215], v[104:107], v[32:35], v[212:215]
	v_max3_f32 v153, v132, v133, v134
	v_max3_f32 v154, v135, v136, v137
	v_mfma_f32_16x16x32_bf16 v[216:219], v[108:111], v[28:31], v[236:239]
	v_max3_f32 v155, v138, v139, v140
	v_max3_f32 v156, v141, v142, v143
	v_mfma_f32_16x16x32_bf16 v[216:219], v[112:115], v[32:35], v[216:219]
	s_nop 0
	v_max3_f32 v153, v153, v154, v144
	v_max3_f32 v155, v155, v156, v145
	v_max3_f32 v153, v153, v155, v146
	v_max_f32_e32 v153, v153, v147
	v_cmp_lt_f32_e32 vcc, 0x41000000, v153
	v_mfma_f32_16x16x32_bf16 v[220:223], v[116:119], v[28:31], v[236:239]
	s_cbranch_vccnz .Lgqa_rare0_gb
; template <int DK>
; DEVI void attn_tile(const char* kb, const char* vb, const bool first, const bf16x8 (&qf)[2][DK / 32], f32x4 (&o)[2][4],
;                     float (&mrun)[2], float (&lsum)[2], const int l15, const int quad) {
;     ...
;       float rm = fmaxf(mx, __shfl_xor(mx, 16));
;       rm = fmaxf(rm, __shfl_xor(rm, 32));
;       const float delta = first ? rm : fmaxf(rm, 0.f);
;       const float alpha = first ? 1.f : ex2(-delta);
;       mrun[qt] += delta;
;       lsum[qt] *= alpha;
; #pragma unroll
;       for (int ks = 0; ks < 4; ++ks)
; #pragma unroll
;         for (int j = 0; j < 4; ++j) s[qt][ks][j] -= delta;
; #pragma unroll
;       for (int dd = 0; dd < 4; ++dd)
; #pragma unroll
;         for (int j = 0; j < 4; ++j) o[qt][dd][j] *= alpha;
;     }
;     float ps = 0.f;
; #pragma unroll
;     for (int ks = 0; ks < 4; ++ks)
; #pragma unroll
;       for (int j = 0; j < 4; ++j) { float pv = ex2(s[qt][ks][j]); s[qt][ks][j] = pv; ps += pv; }
;     lsum[qt] += ps;
; #pragma unroll
;     for (int k2 = 0; k2 < 2; ++k2) {
;       u32x4 wv;
;       wv[0] = pack2(s[qt][2 * k2][0], s[qt][2 * k2][1]);
;       wv[1] = pack2(s[qt][2 * k2][2], s[qt][2 * k2][3]);
;       wv[2] = pack2(s[qt][2 * k2 + 1][0], s[qt][2 * k2 + 1][1]);
;       wv[3] = pack2(s[qt][2 * k2 + 1][2], s[qt][2 * k2 + 1][3]);
;       pf[qt][k2] = as_bf8(wv);
;     }
;   }
; #pragma unroll
;   for (int dd = 0; dd < 4; ++dd)
; #pragma unroll
;     for (int k2 = 0; k2 < 2; ++k2) {
;       u32x2 lo = *reinterpret_cast<const u32x2*>(vb + (dd * 16 + l15) * 144 + (k2 * 32 + quad * 4) * 2);
;       u32x2 hi = *reinterpret_cast<const u32x2*>(vb + (dd * 16 + l15) * 144 + (k2 * 32 + 16 + quad * 4) * 2);
;       u32x4 vv = {lo[0], lo[1], hi[0], hi[1]};
;       bf16x8 vf = as_bf8(vv);
;       o[0][dd] = mfma16(vf, pf[0][k2], o[0][dd]);
;       o[1][dd] = mfma16(vf, pf[1][k2], o[1][dd]);
;     }
; template <int DK, int QP>
; DEVI void attn_item(const bf* __restrict__ Q, const bf* __restrict__ Kp, const bf* __restrict__ Vt, bf* __restrict__ outp  ,
;                     long row_base, int j0, int nkeys, char* smem) {
;     ...
;   ALOAD(rkA, rvA, 0);
;   AWRITE(rkA, rvA, 0);
;   __syncthreads();
;   for (int t = 0; t < nt; ++t) {
;     ALOAD(rkA, rvA, min(t + 1, nt - 1));
;     const char* kb = smem + (t & 1) * STG;
; #pragma unroll
;     for (int pr = 0; pr < QP; ++pr) {
.Lgqa_join0_gb:
	v_add_u32_e32 v208, s18, v169
	ds_read_b64 v[100:101], v208 offset:0
	ds_read_b64 v[102:103], v208 offset:32
	ds_read_b64 v[104:105], v208 offset:2304
	ds_read_b64 v[106:107], v208 offset:2336
	ds_read_b64 v[108:109], v208 offset:4608
	ds_read_b64 v[110:111], v208 offset:4640
	ds_read_b64 v[112:113], v208 offset:6912
	ds_read_b64 v[114:115], v208 offset:6944
	v_exp_f32_e32 v132, v132
	v_exp_f32_e32 v133, v133
	v_exp_f32_e32 v134, v134
	v_exp_f32_e32 v135, v135
	v_add_f32_e32 v154, v132, v133
	v_exp_f32_e32 v136, v136
	v_add_f32_e32 v155, v134, v135
	v_exp_f32_e32 v137, v137
	v_exp_f32_e32 v138, v138
	v_add_f32_e32 v154, v154, v136
	v_mfma_f32_16x16x32_bf16 v[220:223], v[120:123], v[32:35], v[220:223]
	v_exp_f32_e32 v139, v139
	v_add_f32_e32 v155, v155, v137
	v_exp_f32_e32 v140, v140
	v_add_f32_e32 v154, v154, v138
	v_exp_f32_e32 v141, v141
	v_add_f32_e32 v155, v155, v139
	v_exp_f32_e32 v142, v142
	v_add_f32_e32 v154, v154, v140
	v_exp_f32_e32 v143, v143
	v_add_f32_e32 v155, v155, v141
	v_mfma_f32_16x16x32_bf16 v[224:227], v[124:127], v[28:31], v[236:239]
	v_exp_f32_e32 v144, v144
	v_add_f32_e32 v154, v154, v142
	v_exp_f32_e32 v145, v145
	v_add_f32_e32 v155, v155, v143
	v_exp_f32_e32 v146, v146
	v_add_f32_e32 v154, v154, v144
	v_exp_f32_e32 v147, v147
	v_add_f32_e32 v155, v155, v145
	v_add_f32_e32 v154, v154, v146
	v_add_f32_e32 v155, v155, v147
	v_mfma_f32_16x16x32_bf16 v[224:227], v[128:131], v[32:35], v[224:227]
	v_add_f32_e32 v154, v154, v155
	v_add_f32_e32 v174, v174, v154
	v_cvt_pk_bf16_f32 v228, v132, v133
	v_cvt_pk_bf16_f32 v229, v134, v135
	v_cvt_pk_bf16_f32 v230, v136, v137
	v_cvt_pk_bf16_f32 v231, v138, v139
	v_cvt_pk_bf16_f32 v232, v140, v141
	v_cvt_pk_bf16_f32 v233, v142, v143
	v_cvt_pk_bf16_f32 v234, v144, v145
	v_cvt_pk_bf16_f32 v235, v146, v147
	ds_read_b64 v[116:117], v208 offset:64
	ds_read_b64 v[118:119], v208 offset:96
	ds_read_b64 v[120:121], v208 offset:2368
	ds_read_b64 v[122:123], v208 offset:2400
	ds_read_b64 v[124:125], v208 offset:4672
	ds_read_b64 v[126:127], v208 offset:4704
	ds_read_b64 v[128:129], v208 offset:6976
	ds_read_b64 v[130:131], v208 offset:7008
	v_max3_f32 v153, v212, v213, v214
	v_max3_f32 v154, v215, v216, v217
	v_max3_f32 v155, v218, v219, v220
	v_max3_f32 v156, v221, v222, v223
	s_setprio 0
	s_waitcnt lgkmcnt(12)
	v_mfma_f32_16x16x32_bf16 v[72:75], v[100:103], v[228:231], v[72:75]
	v_max3_f32 v153, v153, v154, v224
	v_max3_f32 v155, v155, v156, v225
	v_mfma_f32_16x16x32_bf16 v[80:83], v[104:107], v[228:231], v[80:83]
	v_max3_f32 v153, v153, v155, v226
	v_max_f32_e32 v153, v153, v227
	v_cmp_lt_f32_e32 vcc, 0x41000000, v153
	s_waitcnt lgkmcnt(8)
	v_mfma_f32_16x16x32_bf16 v[88:91], v[108:111], v[228:231], v[88:91]
	s_cbranch_vccnz .Lgqa_rare1_gb
.Lgqa_join1_gb:
	v_exp_f32_e32 v212, v212
	v_exp_f32_e32 v213, v213
	v_exp_f32_e32 v214, v214
	v_exp_f32_e32 v215, v215
	v_add_f32_e32 v154, v212, v213
	v_exp_f32_e32 v216, v216
	v_mfma_f32_16x16x32_bf16 v[96:99], v[112:115], v[228:231], v[96:99]
	v_add_f32_e32 v155, v214, v215
	v_exp_f32_e32 v217, v217
	v_exp_f32_e32 v218, v218
	v_add_f32_e32 v154, v154, v216
	v_exp_f32_e32 v219, v219
	v_add_f32_e32 v155, v155, v217
	v_exp_f32_e32 v220, v220
	s_waitcnt lgkmcnt(4)
	v_mfma_f32_16x16x32_bf16 v[72:75], v[116:119], v[232:235], v[72:75]
	v_add_f32_e32 v154, v154, v218
	v_exp_f32_e32 v221, v221
	v_add_f32_e32 v155, v155, v219
	v_exp_f32_e32 v222, v222
	v_add_f32_e32 v154, v154, v220
	v_exp_f32_e32 v223, v223
	v_add_f32_e32 v155, v155, v221
	v_mfma_f32_16x16x32_bf16 v[80:83], v[120:123], v[232:235], v[80:83]
	v_exp_f32_e32 v224, v224
	v_add_f32_e32 v154, v154, v222
	v_exp_f32_e32 v225, v225
	v_add_f32_e32 v155, v155, v223
	v_exp_f32_e32 v226, v226
	v_add_f32_e32 v154, v154, v224
	s_waitcnt lgkmcnt(0)
	v_mfma_f32_16x16x32_bf16 v[88:91], v[124:127], v[232:235], v[88:91]
	v_exp_f32_e32 v227, v227
	v_add_f32_e32 v155, v155, v225
	v_add_f32_e32 v154, v154, v226
	v_add_f32_e32 v155, v155, v227
	v_add_f32_e32 v154, v154, v155
	v_add_f32_e32 v210, v210, v154
	v_cvt_pk_bf16_f32 v236, v212, v213
	v_mfma_f32_16x16x32_bf16 v[96:99], v[128:131], v[232:235], v[96:99]
	v_cvt_pk_bf16_f32 v237, v214, v215
	v_cvt_pk_bf16_f32 v238, v216, v217
	v_cvt_pk_bf16_f32 v239, v218, v219
	v_cvt_pk_bf16_f32 v240, v220, v221
	v_cvt_pk_bf16_f32 v241, v222, v223
	v_cvt_pk_bf16_f32 v242, v224, v225
	v_cvt_pk_bf16_f32 v243, v226, v227
	s_nop 0
	v_mfma_f32_16x16x32_bf16 v[68:71], v[100:103], v[236:239], v[68:71]
	v_mfma_f32_16x16x32_bf16 v[76:79], v[104:107], v[236:239], v[76:79]
	s_xor_b32 s18, s18, 0x4c00
	v_xor_b32_e32 v228, 0x80000000, v159
	v_mov_b32_e32 v229, v228
	v_mfma_f32_16x16x32_bf16 v[84:87], v[108:111], v[236:239], v[84:87]
	v_mov_b32_e32 v230, v228
	v_mov_b32_e32 v231, v228
	v_mfma_f32_16x16x32_bf16 v[92:95], v[112:115], v[236:239], v[92:95]
	v_add_u32_e32 v209, s18, v170
	v_add_u32_e32 v208, s18, v171
	v_mfma_f32_16x16x32_bf16 v[68:71], v[116:119], v[240:243], v[68:71]
	v_mfma_f32_16x16x32_bf16 v[76:79], v[120:123], v[240:243], v[76:79]
	s_waitcnt vmcnt(2)
	ds_write_b128 v209, v[192:195]
	ds_write_b128 v208, v[196:199]
	v_mfma_f32_16x16x32_bf16 v[84:87], v[124:127], v[240:243], v[84:87]
	v_add_u32_e32 v209, s18, v177
	v_mfma_f32_16x16x32_bf16 v[92:95], v[128:131], v[240:243], v[92:95]
	s_waitcnt vmcnt(0)
	ds_write_b128 v209, v[244:247] offset:10240
	ds_write_b128 v209, v[164:167] offset:14848
	v_xor_b32_e32 v236, 0x80000000, v157
	v_mov_b32_e32 v237, v236
	v_mov_b32_e32 v238, v236
	v_mov_b32_e32 v239, v236
	s_add_i32 s11, s11, 1
	s_cmp_lg_u32 s11, s3
	s_waitcnt lgkmcnt(0)
	s_barrier
	s_cbranch_scc1 .Lgqa_loop_g
	s_branch .Lgqa_exit_g

; DEVI f32x4 mfma16(bf16x8 a, bf16x8 b, f32x4 c) { return __builtin_amdgcn_mfma_f32_16x16x32_bf16(a, b, c, 0, 0, 0); }
; template <int DK>
; DEVI void attn_tile(const char* kb, const char* vb, const bool first, const bf16x8 (&qf)[2][DK / 32], f32x4 (&o)[2][4],
;                     float (&mrun)[2], float (&lsum)[2], const int l15, const int quad) {
;     ...
;   for (int qt = 0; qt < 2; ++qt)
; #pragma unroll
;     for (int ks = 0; ks < 4; ++ks) { const float nm = -mrun[qt]; s[qt][ks] = f32x4{nm, nm, nm, nm}; }
; #pragma unroll
;   for (int ks = 0; ks < 4; ++ks)
; #pragma unroll
;     for (int kk = 0; kk < NKK; ++kk) {
;       bf16x8 kf = *reinterpret_cast<const bf16x8*>(kb + (ks * 16 + l15) * KSTR + (kk * 32 + quad * 8) * 2);
;       s[0][ks] = mfma16(kf, qf[0][kk], s[0][ks]);
;       s[1][ks] = mfma16(kf, qf[1][kk], s[1][ks]);
;     }
;   bf16x8 pf[2][2];
; #pragma unroll
;   for (int qt = 0; qt < 2; ++qt) {
;     float mx = fmaxf(fmaxf(s[qt][0][0], s[qt][0][1]), fmaxf(s[qt][0][2], s[qt][0][3]));
; #pragma unroll
;     for (int ks = 1; ks < 4; ++ks) mx = fmaxf(mx, fmaxf(fmaxf(s[qt][ks][0], s[qt][ks][1]), fmaxf(s[qt][ks][2], s[qt][ks][3])));
;     if (__any(first || (mx > 8.f))) {
; template <int DK, int QP>
; DEVI void attn_item(const bf* __restrict__ Q, const bf* __restrict__ Kp, const bf* __restrict__ Vt, bf* __restrict__ outp  ,
;                     long row_base, int j0, int nkeys, char* smem) {
;     ...
;   for (int t = 0; t < nt; ++t) {
;     ALOAD(rkA, rvA, min(t + 1, nt - 1));
;     const char* kb = smem + (t & 1) * STG;
.Lmla_loop_a:
	v_add_u32_e32 v148, s18, v209
	global_load_dwordx4 v[224:227], v167, s[12:13]
	global_load_dwordx4 v[228:231], v172, s[12:13]
	global_load_dwordx4 v[232:235], v173, s[12:13]
	ds_read_b128 v[60:63], v148
	ds_read_b128 v[64:67], v148 offset:64
	ds_read_b128 v[68:71], v148 offset:128
	global_load_dwordx4 v[168:171], v174, s[22:23]
	global_load_dwordx4 v[160:163], v175, s[22:23]
	ds_read_b128 v[72:75], v148 offset:3584
	ds_read_b128 v[76:79], v148 offset:3648
	ds_read_b128 v[80:83], v148 offset:3712
	ds_read_b128 v[84:87], v148 offset:7168
	ds_read_b128 v[88:91], v148 offset:7232
	ds_read_b128 v[92:95], v148 offset:7296
	ds_read_b128 v[96:99], v148 offset:10752
	ds_read_b128 v[100:103], v148 offset:10816
	ds_read_b128 v[104:107], v148 offset:10880
	s_add_i32 s96, s11, 2
	s_cmp_lt_i32 s96, s24
	s_cselect_b32 s96, 0x3000, 0
	s_cselect_b32 s17, 0x80, 0
	s_add_u32 s12, s12, s96
	s_addc_u32 s13, s13, 0
	s_add_u32 s22, s22, s17
	s_addc_u32 s23, s23, 0
	s_setprio 1
	s_waitcnt lgkmcnt(11)
	v_mfma_f32_16x16x32_bf16 v[108:111], v[60:63], v[4:7], v[204:207]
	s_waitcnt lgkmcnt(9)
	v_mfma_f32_16x16x32_bf16 v[108:111], v[64:67], v[8:11], v[108:111]
	v_mfma_f32_16x16x32_bf16 v[108:111], v[68:71], v[12:15], v[108:111]
	s_waitcnt lgkmcnt(6)
	v_mfma_f32_16x16x32_bf16 v[112:115], v[72:75], v[4:7], v[204:207]
	v_mfma_f32_16x16x32_bf16 v[112:115], v[76:79], v[8:11], v[112:115]
	v_mfma_f32_16x16x32_bf16 v[112:115], v[80:83], v[12:15], v[112:115]
	s_waitcnt lgkmcnt(3)
	v_mfma_f32_16x16x32_bf16 v[116:119], v[84:87], v[4:7], v[204:207]
	v_mfma_f32_16x16x32_bf16 v[116:119], v[88:91], v[8:11], v[116:119]
	v_mfma_f32_16x16x32_bf16 v[116:119], v[92:95], v[12:15], v[116:119]
	s_waitcnt lgkmcnt(0)
	v_mfma_f32_16x16x32_bf16 v[120:123], v[96:99], v[4:7], v[204:207]
	v_mfma_f32_16x16x32_bf16 v[120:123], v[100:103], v[8:11], v[120:123]
	v_mfma_f32_16x16x32_bf16 v[120:123], v[104:107], v[12:15], v[120:123]
	v_mfma_f32_16x16x32_bf16 v[124:127], v[60:63], v[16:19], v[212:215]
	v_mfma_f32_16x16x32_bf16 v[124:127], v[64:67], v[20:23], v[124:127]
	v_max3_f32 v150, v108, v109, v110
	v_max3_f32 v151, v111, v112, v113
	v_mfma_f32_16x16x32_bf16 v[124:127], v[68:71], v[24:27], v[124:127]
	v_max3_f32 v176, v114, v115, v116
	v_max3_f32 v177, v117, v118, v119
	v_mfma_f32_16x16x32_bf16 v[128:131], v[72:75], v[16:19], v[212:215]
	s_nop 0
	v_max3_f32 v150, v150, v151, v120
	v_max3_f32 v176, v176, v177, v121
	v_mfma_f32_16x16x32_bf16 v[128:131], v[76:79], v[20:23], v[128:131]
	v_max3_f32 v150, v150, v176, v122
	v_max_f32_e32 v150, v150, v123
	v_cmp_lt_f32_e32 vcc, 0x41000000, v150
	v_mfma_f32_16x16x32_bf16 v[128:131], v[80:83], v[24:27], v[128:131]
	s_cbranch_vccnz .Lmla_rare0_a
; DEVI unsigned pack2(float a, float b) { f32x2_t v = {a, b}; bf16x2_t r = __builtin_convertvector(v, bf16x2_t); return *reinterpret_cast<unsigned*>(&r); }
; DEVI float ex2(float x) { return __builtin_amdgcn_exp2f(x); }
; template <int DK>
; DEVI void attn_tile(const char* kb, const char* vb, const bool first, const bf16x8 (&qf)[2][DK / 32], f32x4 (&o)[2][4],
;                     float (&mrun)[2], float (&lsum)[2], const int l15, const int quad) {
;     ...
;       float rm = fmaxf(mx, __shfl_xor(mx, 16));
;       rm = fmaxf(rm, __shfl_xor(rm, 32));
;       const float delta = first ? rm : fmaxf(rm, 0.f);
;       const float alpha = first ? 1.f : ex2(-delta);
;       mrun[qt] += delta;
;       lsum[qt] *= alpha;
; #pragma unroll
;       for (int ks = 0; ks < 4; ++ks)
; #pragma unroll
;         for (int j = 0; j < 4; ++j) s[qt][ks][j] -= delta;
; #pragma unroll
;       for (int dd = 0; dd < 4; ++dd)
; #pragma unroll
;         for (int j = 0; j < 4; ++j) o[qt][dd][j] *= alpha;
;     }
;     float ps = 0.f;
; #pragma unroll
;     for (int ks = 0; ks < 4; ++ks)
; #pragma unroll
;       for (int j = 0; j < 4; ++j) { float pv = ex2(s[qt][ks][j]); s[qt][ks][j] = pv; ps += pv; }
;     lsum[qt] += ps;
; #pragma unroll
;     for (int k2 = 0; k2 < 2; ++k2) {
;       u32x4 wv;
;       wv[0] = pack2(s[qt][2 * k2][0], s[qt][2 * k2][1]);
;       wv[1] = pack2(s[qt][2 * k2][2], s[qt][2 * k2][3]);
;       wv[2] = pack2(s[qt][2 * k2 + 1][0], s[qt][2 * k2 + 1][1]);
;       wv[3] = pack2(s[qt][2 * k2 + 1][2], s[qt][2 * k2 + 1][3]);
;       pf[qt][k2] = as_bf8(wv);
;     }
;   }
; #pragma unroll
;   for (int dd = 0; dd < 4; ++dd)
; #pragma unroll
;     for (int k2 = 0; k2 < 2; ++k2) {
;       u32x2 lo = *reinterpret_cast<const u32x2*>(vb + (dd * 16 + l15) * 144 + (k2 * 32 + quad * 4) * 2);
;       u32x2 hi = *reinterpret_cast<const u32x2*>(vb + (dd * 16 + l15) * 144 + (k2 * 32 + 16 + quad * 4) * 2);
;       u32x4 vv = {lo[0], lo[1], hi[0], hi[1]};
;       bf16x8 vf = as_bf8(vv);
;       o[0][dd] = mfma16(vf, pf[0][k2], o[0][dd]);
;       o[1][dd] = mfma16(vf, pf[1][k2], o[1][dd]);
;     }
; template <int DK, int QP>
; DEVI void attn_item(const bf* __restrict__ Q, const bf* __restrict__ Kp, const bf* __restrict__ Vt, bf* __restrict__ outp  ,
;                     long row_base, int j0, int nkeys, char* smem) {
;     ...
;     AWRITE(rkA, rvA, (t + 1) & 1);
;     __syncthreads();
.Lmla_join0_a:
	v_add_u32_e32 v149, s18, v210
	ds_read_b64 v[60:61], v149 offset:0
	ds_read_b64 v[62:63], v149 offset:32
	ds_read_b64 v[64:65], v149 offset:2304
	ds_read_b64 v[66:67], v149 offset:2336
	ds_read_b64 v[68:69], v149 offset:4608
	ds_read_b64 v[70:71], v149 offset:4640
	ds_read_b64 v[72:73], v149 offset:6912
	ds_read_b64 v[74:75], v149 offset:6944
	v_exp_f32_e32 v108, v108
	v_exp_f32_e32 v109, v109
	v_exp_f32_e32 v110, v110
	v_exp_f32_e32 v111, v111
	v_add_f32_e32 v151, v108, v109
	v_mfma_f32_16x16x32_bf16 v[132:135], v[84:87], v[16:19], v[212:215]
	v_exp_f32_e32 v112, v112
	v_add_f32_e32 v176, v110, v111
	v_exp_f32_e32 v113, v113
	v_exp_f32_e32 v114, v114
	v_add_f32_e32 v151, v151, v112
	v_exp_f32_e32 v115, v115
	v_mfma_f32_16x16x32_bf16 v[132:135], v[88:91], v[20:23], v[132:135]
	v_add_f32_e32 v176, v176, v113
	v_exp_f32_e32 v116, v116
	v_add_f32_e32 v151, v151, v114
	v_exp_f32_e32 v117, v117
	v_add_f32_e32 v176, v176, v115
	v_exp_f32_e32 v118, v118
	ds_read_b64 v[76:77], v149 offset:64
	ds_read_b64 v[78:79], v149 offset:96
	ds_read_b64 v[80:81], v149 offset:2368
	ds_read_b64 v[82:83], v149 offset:2400
	ds_read_b64 v[84:85], v149 offset:4672
	ds_read_b64 v[86:87], v149 offset:4704
	ds_read_b64 v[88:89], v149 offset:6976
	ds_read_b64 v[90:91], v149 offset:7008
	v_mfma_f32_16x16x32_bf16 v[132:135], v[92:95], v[24:27], v[132:135]
	v_add_f32_e32 v151, v151, v116
	v_exp_f32_e32 v119, v119
	v_add_f32_e32 v176, v176, v117
	v_exp_f32_e32 v120, v120
	v_add_f32_e32 v151, v151, v118
	v_mfma_f32_16x16x32_bf16 v[136:139], v[96:99], v[16:19], v[212:215]
	v_exp_f32_e32 v121, v121
	v_add_f32_e32 v176, v176, v119
	v_exp_f32_e32 v122, v122
	v_add_f32_e32 v151, v151, v120
	v_exp_f32_e32 v123, v123
	v_add_f32_e32 v176, v176, v121
	v_mfma_f32_16x16x32_bf16 v[136:139], v[100:103], v[20:23], v[136:139]
	v_add_f32_e32 v151, v151, v122
	v_add_f32_e32 v176, v176, v123
	v_add_f32_e32 v151, v151, v176
	v_add_f32_e32 v166, v166, v151
	v_cvt_pk_bf16_f32 v140, v108, v109
	v_cvt_pk_bf16_f32 v141, v110, v111
	v_mfma_f32_16x16x32_bf16 v[136:139], v[104:107], v[24:27], v[136:139]
	v_cvt_pk_bf16_f32 v142, v112, v113
	v_cvt_pk_bf16_f32 v143, v114, v115
	v_cvt_pk_bf16_f32 v144, v116, v117
	v_cvt_pk_bf16_f32 v145, v118, v119
	v_cvt_pk_bf16_f32 v146, v120, v121
	v_cvt_pk_bf16_f32 v147, v122, v123
	s_setprio 0
	s_waitcnt lgkmcnt(12)
	v_mfma_f32_16x16x32_bf16 v[56:59], v[60:63], v[140:143], v[56:59]
	v_max3_f32 v150, v124, v125, v126
	v_max3_f32 v151, v127, v128, v129
	v_mfma_f32_16x16x32_bf16 v[48:51], v[64:67], v[140:143], v[48:51]
	v_max3_f32 v176, v130, v131, v132
	v_max3_f32 v177, v133, v134, v135
	v_max3_f32 v150, v150, v151, v136
	v_max3_f32 v176, v176, v177, v137
	s_waitcnt lgkmcnt(8)
	v_mfma_f32_16x16x32_bf16 v[44:47], v[68:71], v[140:143], v[44:47]
	v_max3_f32 v150, v150, v176, v138
	v_max_f32_e32 v150, v150, v139
	v_cmp_lt_f32_e32 vcc, 0x41000000, v150
	v_mfma_f32_16x16x32_bf16 v[52:55], v[72:75], v[140:143], v[52:55]
	s_cbranch_vccnz .Lmla_rare1_a
.Lmla_join1_a:
	v_exp_f32_e32 v124, v124
	v_exp_f32_e32 v125, v125
	v_exp_f32_e32 v126, v126
	v_exp_f32_e32 v127, v127
	v_add_f32_e32 v151, v124, v125
	v_exp_f32_e32 v128, v128
	v_add_f32_e32 v176, v126, v127
	v_exp_f32_e32 v129, v129
	s_waitcnt lgkmcnt(4)
	v_mfma_f32_16x16x32_bf16 v[56:59], v[76:79], v[144:147], v[56:59]
	v_exp_f32_e32 v130, v130
	v_add_f32_e32 v151, v151, v128
	v_exp_f32_e32 v131, v131
	v_add_f32_e32 v176, v176, v129
	v_exp_f32_e32 v132, v132
	v_add_f32_e32 v151, v151, v130
	v_exp_f32_e32 v133, v133
	v_add_f32_e32 v176, v176, v131
	v_mfma_f32_16x16x32_bf16 v[48:51], v[80:83], v[144:147], v[48:51]
	v_exp_f32_e32 v134, v134
	v_add_f32_e32 v151, v151, v132
	v_exp_f32_e32 v135, v135
	v_add_f32_e32 v176, v176, v133
	v_exp_f32_e32 v136, v136
	v_add_f32_e32 v151, v151, v134
	v_exp_f32_e32 v137, v137
	v_add_f32_e32 v176, v176, v135
	s_waitcnt lgkmcnt(0)
	v_mfma_f32_16x16x32_bf16 v[44:47], v[84:87], v[144:147], v[44:47]
	v_exp_f32_e32 v138, v138
	v_add_f32_e32 v151, v151, v136
	v_exp_f32_e32 v139, v139
	v_add_f32_e32 v176, v176, v137
	v_add_f32_e32 v151, v151, v138
	v_add_f32_e32 v176, v176, v139
	v_add_f32_e32 v151, v151, v176
	v_add_f32_e32 v153, v153, v151
	v_mfma_f32_16x16x32_bf16 v[52:55], v[88:91], v[144:147], v[52:55]
	v_cvt_pk_bf16_f32 v216, v124, v125
	v_cvt_pk_bf16_f32 v217, v126, v127
	v_cvt_pk_bf16_f32 v218, v128, v129
	v_cvt_pk_bf16_f32 v219, v130, v131
	v_cvt_pk_bf16_f32 v220, v132, v133
	v_cvt_pk_bf16_f32 v221, v134, v135
	v_cvt_pk_bf16_f32 v222, v136, v137
	v_cvt_pk_bf16_f32 v223, v138, v139
	s_xor_b32 s18, s18, 0x5c00
	s_nop 0
	v_mfma_f32_16x16x32_bf16 v[32:35], v[60:63], v[216:219], v[32:35]
	v_mfma_f32_16x16x32_bf16 v[28:31], v[64:67], v[216:219], v[28:31]
	v_add_u32_e32 v150, s18, v155
	v_add_u32_e32 v151, s18, v157
	v_mfma_f32_16x16x32_bf16 v[36:39], v[68:71], v[216:219], v[36:39]
	v_mfma_f32_16x16x32_bf16 v[40:43], v[72:75], v[216:219], v[40:43]
	s_waitcnt vmcnt(2)
	ds_write_b128 v150, v[224:227]
	ds_write_b128 v151, v[228:231]
	v_mfma_f32_16x16x32_bf16 v[32:35], v[76:79], v[220:223], v[32:35]
	v_add_u32_e32 v150, s18, v159
	v_add_u32_e32 v151, s18, v165
	v_mfma_f32_16x16x32_bf16 v[28:31], v[80:83], v[220:223], v[28:31]
	v_mfma_f32_16x16x32_bf16 v[36:39], v[84:87], v[220:223], v[36:39]
	ds_write_b128 v150, v[232:235]
	v_mfma_f32_16x16x32_bf16 v[40:43], v[88:91], v[220:223], v[40:43]
	s_waitcnt vmcnt(0)
	ds_write_b128 v151, v[168:171] offset:14336
	ds_write_b128 v151, v[160:163] offset:18944
	s_add_i32 s11, s11, 1
	s_cmp_lg_u32 s11, s24
	s_waitcnt lgkmcnt(0)
	s_barrier
	s_cbranch_scc1 .Lmla_loop_a
	s_branch .Lmla_exit_a
